# P0 weight transposes: load loop unrolled with two register sets, 16 loads in flight under counted vmcnt
# baseline (speedup 1.0000x reference)
.LBB0_17:
	v_lshl_add_u64 v[52:53], v[32:33], 0, s[54:55]
	v_lshl_add_u64 v[54:55], v[30:31], 0, s[54:55]
	v_lshl_add_u64 v[56:57], v[28:29], 0, s[54:55]
	v_lshl_add_u64 v[58:59], v[26:27], 0, s[54:55]
	v_lshl_add_u64 v[60:61], v[24:25], 0, s[54:55]
	v_lshl_add_u64 v[62:63], v[22:23], 0, s[54:55]
	v_lshl_add_u64 v[64:65], v[20:21], 0, s[54:55]
	v_lshl_add_u64 v[66:67], v[18:19], 0, s[54:55]
	global_load_dword v52, v[52:53], off nt
	global_load_dword v53, v[54:55], off nt
	global_load_dword v54, v[56:57], off nt
	global_load_dword v55, v[58:59], off nt
	global_load_dword v56, v[60:61], off nt
	global_load_dword v57, v[62:63], off nt
	global_load_dword v58, v[64:65], off nt
	global_load_dword v59, v[66:67], off nt
	s_add_u32 s54, s54, 0x20000
	s_addc_u32 s55, s55, 0
	v_lshl_add_u64 v[110:111], v[32:33], 0, s[54:55]
	v_lshl_add_u64 v[112:113], v[30:31], 0, s[54:55]
	v_lshl_add_u64 v[114:115], v[28:29], 0, s[54:55]
	v_lshl_add_u64 v[116:117], v[26:27], 0, s[54:55]
	v_lshl_add_u64 v[118:119], v[24:25], 0, s[54:55]
	v_lshl_add_u64 v[120:121], v[22:23], 0, s[54:55]
	v_lshl_add_u64 v[122:123], v[20:21], 0, s[54:55]
	v_lshl_add_u64 v[124:125], v[18:19], 0, s[54:55]
	global_load_dword v110, v[110:111], off nt
	global_load_dword v111, v[112:113], off nt
	global_load_dword v112, v[114:115], off nt
	global_load_dword v113, v[116:117], off nt
	global_load_dword v114, v[118:119], off nt
	global_load_dword v115, v[120:121], off nt
	global_load_dword v116, v[122:123], off nt
	global_load_dword v117, v[124:125], off nt
	s_add_u32 s54, s54, 0x20000
	s_addc_u32 s55, s55, 0
	v_add_u32_e32 v60, 0x400, v4
	s_waitcnt vmcnt(14)
	ds_write2_b32 v4, v52, v53 offset1:66
	s_waitcnt vmcnt(12)
	ds_write2_b32 v4, v54, v55 offset0:132 offset1:198
	s_waitcnt vmcnt(10)
	ds_write2_b32 v60, v56, v57 offset0:8 offset1:74
	s_waitcnt vmcnt(8)
	ds_write2_b32 v60, v58, v59 offset0:140 offset1:206
	v_add_u32_e32 v4, 0x840, v4
	v_lshl_add_u64 v[52:53], v[32:33], 0, s[54:55]
	v_lshl_add_u64 v[54:55], v[30:31], 0, s[54:55]
	v_lshl_add_u64 v[56:57], v[28:29], 0, s[54:55]
	v_lshl_add_u64 v[58:59], v[26:27], 0, s[54:55]
	v_lshl_add_u64 v[60:61], v[24:25], 0, s[54:55]
	v_lshl_add_u64 v[62:63], v[22:23], 0, s[54:55]
	v_lshl_add_u64 v[64:65], v[20:21], 0, s[54:55]
	v_lshl_add_u64 v[66:67], v[18:19], 0, s[54:55]
	global_load_dword v52, v[52:53], off nt
	global_load_dword v53, v[54:55], off nt
	global_load_dword v54, v[56:57], off nt
	global_load_dword v55, v[58:59], off nt
	global_load_dword v56, v[60:61], off nt
	global_load_dword v57, v[62:63], off nt
	global_load_dword v58, v[64:65], off nt
	global_load_dword v59, v[66:67], off nt
	s_add_u32 s54, s54, 0x20000
	s_addc_u32 s55, s55, 0
	v_add_u32_e32 v118, 0x400, v4
	s_waitcnt vmcnt(14)
	ds_write2_b32 v4, v110, v111 offset1:66
	s_waitcnt vmcnt(12)
	ds_write2_b32 v4, v112, v113 offset0:132 offset1:198
	s_waitcnt vmcnt(10)
	ds_write2_b32 v118, v114, v115 offset0:8 offset1:74
	s_waitcnt vmcnt(8)
	ds_write2_b32 v118, v116, v117 offset0:140 offset1:206
	v_add_u32_e32 v4, 0x840, v4
	v_lshl_add_u64 v[110:111], v[32:33], 0, s[54:55]
	v_lshl_add_u64 v[112:113], v[30:31], 0, s[54:55]
	v_lshl_add_u64 v[114:115], v[28:29], 0, s[54:55]
	v_lshl_add_u64 v[116:117], v[26:27], 0, s[54:55]
	v_lshl_add_u64 v[118:119], v[24:25], 0, s[54:55]
	v_lshl_add_u64 v[120:121], v[22:23], 0, s[54:55]
	v_lshl_add_u64 v[122:123], v[20:21], 0, s[54:55]
	v_lshl_add_u64 v[124:125], v[18:19], 0, s[54:55]
	global_load_dword v110, v[110:111], off nt
	global_load_dword v111, v[112:113], off nt
	global_load_dword v112, v[114:115], off nt
	global_load_dword v113, v[116:117], off nt
	global_load_dword v114, v[118:119], off nt
	global_load_dword v115, v[120:121], off nt
	global_load_dword v116, v[122:123], off nt
	global_load_dword v117, v[124:125], off nt
	s_add_u32 s54, s54, 0x20000
	s_addc_u32 s55, s55, 0
	v_add_u32_e32 v60, 0x400, v4
	s_waitcnt vmcnt(14)
	ds_write2_b32 v4, v52, v53 offset1:66
	s_waitcnt vmcnt(12)
	ds_write2_b32 v4, v54, v55 offset0:132 offset1:198
	s_waitcnt vmcnt(10)
	ds_write2_b32 v60, v56, v57 offset0:8 offset1:74
	s_waitcnt vmcnt(8)
	ds_write2_b32 v60, v58, v59 offset0:140 offset1:206
	v_add_u32_e32 v4, 0x840, v4
	v_add_u32_e32 v118, 0x400, v4
	s_waitcnt vmcnt(6)
	ds_write2_b32 v4, v110, v111 offset1:66
	s_waitcnt vmcnt(4)
	ds_write2_b32 v4, v112, v113 offset0:132 offset1:198
	s_waitcnt vmcnt(2)
	ds_write2_b32 v118, v114, v115 offset0:8 offset1:74
	s_waitcnt vmcnt(0)
	ds_write2_b32 v118, v116, v117 offset0:140 offset1:206
	v_add_u32_e32 v4, 0x840, v4
	s_waitcnt lgkmcnt(0)
	ds_read2_b32 v[22:23], v37 offset0:33 offset1:41
	ds_read2_b32 v[24:25], v37 offset1:8
	ds_read2_b32 v[26:27], v37 offset0:66 offset1:74
	ds_read2_b32 v[28:29], v37 offset0:99 offset1:107
	ds_read2_b32 v[30:31], v37 offset0:132 offset1:140
	ds_read2_b32 v[32:33], v37 offset0:165 offset1:173
	ds_read2_b32 v[52:53], v37 offset0:198 offset1:206
	ds_read2_b32 v[54:55], v37 offset0:231 offset1:239
	s_add_i32 s6, s68, 0xaa00
	s_and_b32 s6, s6, 0xffc0
	s_lshl_b32 s6, s6, 1
	v_or_b32_e32 v4, s56, v36
	v_lshl_add_u64 v[56:57], v[6:7], 0, s[6:7]
	v_lshlrev_b32_e32 v4, 12, v4
	s_waitcnt lgkmcnt(6)
	v_cvt_pk_bf16_f32 v18, v24, v22
	s_waitcnt lgkmcnt(4)
	v_cvt_pk_bf16_f32 v19, v26, v28
	s_waitcnt lgkmcnt(2)
	v_cvt_pk_bf16_f32 v20, v30, v32
	s_waitcnt lgkmcnt(0)
	v_cvt_pk_bf16_f32 v21, v52, v54
	v_lshl_add_u64 v[58:59], v[56:57], 0, v[4:5]
	global_store_dwordx4 v[58:59], v[18:21], off nt
	v_or_b32_e32 v4, s56, v38
	v_lshlrev_b32_e32 v4, 12, v4
	v_cvt_pk_bf16_f32 v18, v25, v23
	v_cvt_pk_bf16_f32 v19, v27, v29
	v_cvt_pk_bf16_f32 v20, v31, v33
	v_cvt_pk_bf16_f32 v21, v53, v55
	ds_read2_b32 v[24:25], v37 offset0:49 offset1:57
	ds_read2_b32 v[26:27], v37 offset0:16 offset1:24
	ds_read2_b32 v[28:29], v37 offset0:82 offset1:90
	ds_read2_b32 v[30:31], v37 offset0:115 offset1:123
	ds_read2_b32 v[32:33], v37 offset0:148 offset1:156
	ds_read2_b32 v[52:53], v37 offset0:181 offset1:189
	ds_read2_b32 v[54:55], v37 offset0:214 offset1:222
	ds_read2_b32 v[58:59], v37 offset0:247 offset1:255
	v_lshl_add_u64 v[22:23], v[56:57], 0, v[4:5]
	v_or_b32_e32 v4, s56, v39
	v_lshlrev_b32_e32 v4, 12, v4
	global_store_dwordx4 v[22:23], v[18:21], off nt
	v_lshl_add_u64 v[22:23], v[56:57], 0, v[4:5]
	v_or_b32_e32 v4, s56, v40
	s_waitcnt lgkmcnt(6)
	v_cvt_pk_bf16_f32 v18, v26, v24
	s_waitcnt lgkmcnt(4)
	v_cvt_pk_bf16_f32 v19, v28, v30
	s_waitcnt lgkmcnt(2)
	v_cvt_pk_bf16_f32 v20, v32, v52
	s_waitcnt lgkmcnt(0)
	v_cvt_pk_bf16_f32 v21, v54, v58
	v_lshlrev_b32_e32 v4, 12, v4
	global_store_dwordx4 v[22:23], v[18:21], off nt
	v_lshl_add_u64 v[22:23], v[56:57], 0, v[4:5]
	s_mov_b64 s[54:55], 0
	v_cvt_pk_bf16_f32 v18, v27, v25
	v_cvt_pk_bf16_f32 v19, v29, v31
	v_cvt_pk_bf16_f32 v20, v33, v53
	v_cvt_pk_bf16_f32 v21, v55, v59
	global_store_dwordx4 v[22:23], v[18:21], off nt
	s_waitcnt lgkmcnt(0)

.LBB0_21:
	v_lshl_add_u64 v[52:53], v[32:33], 0, s[54:55]
	v_lshl_add_u64 v[54:55], v[30:31], 0, s[54:55]
	v_lshl_add_u64 v[56:57], v[28:29], 0, s[54:55]
	v_lshl_add_u64 v[58:59], v[26:27], 0, s[54:55]
	v_lshl_add_u64 v[60:61], v[24:25], 0, s[54:55]
	v_lshl_add_u64 v[62:63], v[22:23], 0, s[54:55]
	v_lshl_add_u64 v[64:65], v[20:21], 0, s[54:55]
	v_lshl_add_u64 v[66:67], v[18:19], 0, s[54:55]
	global_load_dword v52, v[52:53], off nt
	global_load_dword v53, v[54:55], off nt
	global_load_dword v54, v[56:57], off nt
	global_load_dword v55, v[58:59], off nt
	global_load_dword v56, v[60:61], off nt
	global_load_dword v57, v[62:63], off nt
	global_load_dword v58, v[64:65], off nt
	global_load_dword v59, v[66:67], off nt
	s_add_u32 s54, s54, 0x20000
	s_addc_u32 s55, s55, 0
	v_lshl_add_u64 v[110:111], v[32:33], 0, s[54:55]
	v_lshl_add_u64 v[112:113], v[30:31], 0, s[54:55]
	v_lshl_add_u64 v[114:115], v[28:29], 0, s[54:55]
	v_lshl_add_u64 v[116:117], v[26:27], 0, s[54:55]
	v_lshl_add_u64 v[118:119], v[24:25], 0, s[54:55]
	v_lshl_add_u64 v[120:121], v[22:23], 0, s[54:55]
	v_lshl_add_u64 v[122:123], v[20:21], 0, s[54:55]
	v_lshl_add_u64 v[124:125], v[18:19], 0, s[54:55]
	global_load_dword v110, v[110:111], off nt
	global_load_dword v111, v[112:113], off nt
	global_load_dword v112, v[114:115], off nt
	global_load_dword v113, v[116:117], off nt
	global_load_dword v114, v[118:119], off nt
	global_load_dword v115, v[120:121], off nt
	global_load_dword v116, v[122:123], off nt
	global_load_dword v117, v[124:125], off nt
	s_add_u32 s54, s54, 0x20000
	s_addc_u32 s55, s55, 0
	v_add_u32_e32 v60, 0x400, v4
	s_waitcnt vmcnt(14)
	ds_write2_b32 v4, v52, v53 offset1:66
	s_waitcnt vmcnt(12)
	ds_write2_b32 v4, v54, v55 offset0:132 offset1:198
	s_waitcnt vmcnt(10)
	ds_write2_b32 v60, v56, v57 offset0:8 offset1:74
	s_waitcnt vmcnt(8)
	ds_write2_b32 v60, v58, v59 offset0:140 offset1:206
	v_add_u32_e32 v4, 0x840, v4
	v_lshl_add_u64 v[52:53], v[32:33], 0, s[54:55]
	v_lshl_add_u64 v[54:55], v[30:31], 0, s[54:55]
	v_lshl_add_u64 v[56:57], v[28:29], 0, s[54:55]
	v_lshl_add_u64 v[58:59], v[26:27], 0, s[54:55]
	v_lshl_add_u64 v[60:61], v[24:25], 0, s[54:55]
	v_lshl_add_u64 v[62:63], v[22:23], 0, s[54:55]
	v_lshl_add_u64 v[64:65], v[20:21], 0, s[54:55]
	v_lshl_add_u64 v[66:67], v[18:19], 0, s[54:55]
	global_load_dword v52, v[52:53], off nt
	global_load_dword v53, v[54:55], off nt
	global_load_dword v54, v[56:57], off nt
	global_load_dword v55, v[58:59], off nt
	global_load_dword v56, v[60:61], off nt
	global_load_dword v57, v[62:63], off nt
	global_load_dword v58, v[64:65], off nt
	global_load_dword v59, v[66:67], off nt
	s_add_u32 s54, s54, 0x20000
	s_addc_u32 s55, s55, 0
	v_add_u32_e32 v118, 0x400, v4
	s_waitcnt vmcnt(14)
	ds_write2_b32 v4, v110, v111 offset1:66
	s_waitcnt vmcnt(12)
	ds_write2_b32 v4, v112, v113 offset0:132 offset1:198
	s_waitcnt vmcnt(10)
	ds_write2_b32 v118, v114, v115 offset0:8 offset1:74
	s_waitcnt vmcnt(8)
	ds_write2_b32 v118, v116, v117 offset0:140 offset1:206
	v_add_u32_e32 v4, 0x840, v4
	v_lshl_add_u64 v[110:111], v[32:33], 0, s[54:55]
	v_lshl_add_u64 v[112:113], v[30:31], 0, s[54:55]
	v_lshl_add_u64 v[114:115], v[28:29], 0, s[54:55]
	v_lshl_add_u64 v[116:117], v[26:27], 0, s[54:55]
	v_lshl_add_u64 v[118:119], v[24:25], 0, s[54:55]
	v_lshl_add_u64 v[120:121], v[22:23], 0, s[54:55]
	v_lshl_add_u64 v[122:123], v[20:21], 0, s[54:55]
	v_lshl_add_u64 v[124:125], v[18:19], 0, s[54:55]
	global_load_dword v110, v[110:111], off nt
	global_load_dword v111, v[112:113], off nt
	global_load_dword v112, v[114:115], off nt
	global_load_dword v113, v[116:117], off nt
	global_load_dword v114, v[118:119], off nt
	global_load_dword v115, v[120:121], off nt
	global_load_dword v116, v[122:123], off nt
	global_load_dword v117, v[124:125], off nt
	s_add_u32 s54, s54, 0x20000
	s_addc_u32 s55, s55, 0
	v_add_u32_e32 v60, 0x400, v4
	s_waitcnt vmcnt(14)
	ds_write2_b32 v4, v52, v53 offset1:66
	s_waitcnt vmcnt(12)
	ds_write2_b32 v4, v54, v55 offset0:132 offset1:198
	s_waitcnt vmcnt(10)
	ds_write2_b32 v60, v56, v57 offset0:8 offset1:74
	s_waitcnt vmcnt(8)
	ds_write2_b32 v60, v58, v59 offset0:140 offset1:206
	v_add_u32_e32 v4, 0x840, v4
	v_add_u32_e32 v118, 0x400, v4
	s_waitcnt vmcnt(6)
	ds_write2_b32 v4, v110, v111 offset1:66
	s_waitcnt vmcnt(4)
	ds_write2_b32 v4, v112, v113 offset0:132 offset1:198
	s_waitcnt vmcnt(2)
	ds_write2_b32 v118, v114, v115 offset0:8 offset1:74
	s_waitcnt vmcnt(0)
	ds_write2_b32 v118, v116, v117 offset0:140 offset1:206
	v_add_u32_e32 v4, 0x840, v4
	s_waitcnt lgkmcnt(0)
	s_add_i32 s6, s68, 0xae00
	ds_read2_b32 v[22:23], v37 offset0:33 offset1:41
	ds_read2_b32 v[24:25], v37 offset1:8
	ds_read2_b32 v[26:27], v37 offset0:66 offset1:74
	ds_read2_b32 v[28:29], v37 offset0:99 offset1:107
	ds_read2_b32 v[30:31], v37 offset0:132 offset1:140
	ds_read2_b32 v[32:33], v37 offset0:165 offset1:173
	ds_read2_b32 v[52:53], v37 offset0:198 offset1:206
	ds_read2_b32 v[54:55], v37 offset0:231 offset1:239
	s_and_b32 s6, s6, 0xffc0
	v_or_b32_e32 v4, s56, v36
	s_lshl_b32 s6, s6, 1
	v_mul_u32_u24_e32 v4, 0xa00, v4
	v_lshl_add_u64 v[56:57], v[8:9], 0, s[6:7]
	v_lshlrev_b32_e32 v4, 1, v4
	v_lshl_add_u64 v[58:59], v[56:57], 0, v[4:5]
	v_or_b32_e32 v4, s56, v38
	s_waitcnt lgkmcnt(6)
	v_cvt_pk_bf16_f32 v18, v24, v22
	s_waitcnt lgkmcnt(4)
	v_cvt_pk_bf16_f32 v19, v26, v28
	s_waitcnt lgkmcnt(2)
	v_cvt_pk_bf16_f32 v20, v30, v32
	s_waitcnt lgkmcnt(0)
	v_cvt_pk_bf16_f32 v21, v52, v54
	v_mul_u32_u24_e32 v4, 0xa00, v4
	global_store_dwordx4 v[58:59], v[18:21], off nt
	v_lshlrev_b32_e32 v4, 1, v4
	s_nop 0
	v_cvt_pk_bf16_f32 v18, v25, v23
	v_cvt_pk_bf16_f32 v19, v27, v29
	v_cvt_pk_bf16_f32 v20, v31, v33
	v_cvt_pk_bf16_f32 v21, v53, v55
	v_lshl_add_u64 v[22:23], v[56:57], 0, v[4:5]
	ds_read2_b32 v[24:25], v37 offset0:16 offset1:24
	ds_read2_b32 v[26:27], v37 offset0:49 offset1:57
	ds_read2_b32 v[28:29], v37 offset0:82 offset1:90
	ds_read2_b32 v[30:31], v37 offset0:115 offset1:123
	ds_read2_b32 v[32:33], v37 offset0:148 offset1:156
	ds_read2_b32 v[52:53], v37 offset0:181 offset1:189
	ds_read2_b32 v[54:55], v37 offset0:214 offset1:222
	ds_read2_b32 v[58:59], v37 offset0:247 offset1:255
	v_or_b32_e32 v4, s56, v39
	v_mul_u32_u24_e32 v4, 0xa00, v4
	v_lshlrev_b32_e32 v4, 1, v4
	global_store_dwordx4 v[22:23], v[18:21], off nt
	v_lshl_add_u64 v[22:23], v[56:57], 0, v[4:5]
	v_or_b32_e32 v4, s56, v40
	v_mul_u32_u24_e32 v4, 0xa00, v4
	s_waitcnt lgkmcnt(6)
	v_cvt_pk_bf16_f32 v18, v24, v26
	s_waitcnt lgkmcnt(4)
	v_cvt_pk_bf16_f32 v19, v28, v30
	s_waitcnt lgkmcnt(2)
	v_cvt_pk_bf16_f32 v20, v32, v52
	s_waitcnt lgkmcnt(0)
	v_cvt_pk_bf16_f32 v21, v54, v58
	v_lshlrev_b32_e32 v4, 1, v4
	global_store_dwordx4 v[22:23], v[18:21], off nt
	v_lshl_add_u64 v[22:23], v[56:57], 0, v[4:5]
	s_nop 0
	v_cvt_pk_bf16_f32 v18, v25, v27
	v_cvt_pk_bf16_f32 v19, v29, v31
	v_cvt_pk_bf16_f32 v20, v33, v53
	v_cvt_pk_bf16_f32 v21, v55, v59
	global_store_dwordx4 v[22:23], v[18:21], off nt
	s_waitcnt lgkmcnt(0)

.LBB0_26:
	v_lshl_add_u64 v[52:53], v[32:33], 0, s[54:55]
	v_lshl_add_u64 v[54:55], v[30:31], 0, s[54:55]
	v_lshl_add_u64 v[56:57], v[28:29], 0, s[54:55]
	v_lshl_add_u64 v[58:59], v[26:27], 0, s[54:55]
	v_lshl_add_u64 v[60:61], v[24:25], 0, s[54:55]
	v_lshl_add_u64 v[62:63], v[22:23], 0, s[54:55]
	v_lshl_add_u64 v[64:65], v[20:21], 0, s[54:55]
	v_lshl_add_u64 v[66:67], v[18:19], 0, s[54:55]
	global_load_dword v52, v[52:53], off nt
	global_load_dword v53, v[54:55], off nt
	global_load_dword v54, v[56:57], off nt
	global_load_dword v55, v[58:59], off nt
	global_load_dword v56, v[60:61], off nt
	global_load_dword v57, v[62:63], off nt
	global_load_dword v58, v[64:65], off nt
	global_load_dword v59, v[66:67], off nt
	s_add_u32 s54, s54, 0x20000
	s_addc_u32 s55, s55, 0
	v_lshl_add_u64 v[110:111], v[32:33], 0, s[54:55]
	v_lshl_add_u64 v[112:113], v[30:31], 0, s[54:55]
	v_lshl_add_u64 v[114:115], v[28:29], 0, s[54:55]
	v_lshl_add_u64 v[116:117], v[26:27], 0, s[54:55]
	v_lshl_add_u64 v[118:119], v[24:25], 0, s[54:55]
	v_lshl_add_u64 v[120:121], v[22:23], 0, s[54:55]
	v_lshl_add_u64 v[122:123], v[20:21], 0, s[54:55]
	v_lshl_add_u64 v[124:125], v[18:19], 0, s[54:55]
	global_load_dword v110, v[110:111], off nt
	global_load_dword v111, v[112:113], off nt
	global_load_dword v112, v[114:115], off nt
	global_load_dword v113, v[116:117], off nt
	global_load_dword v114, v[118:119], off nt
	global_load_dword v115, v[120:121], off nt
	global_load_dword v116, v[122:123], off nt
	global_load_dword v117, v[124:125], off nt
	s_add_u32 s54, s54, 0x20000
	s_addc_u32 s55, s55, 0
	v_add_u32_e32 v60, 0x400, v4
	s_waitcnt vmcnt(14)
	ds_write2_b32 v4, v52, v53 offset1:66
	s_waitcnt vmcnt(12)
	ds_write2_b32 v4, v54, v55 offset0:132 offset1:198
	s_waitcnt vmcnt(10)
	ds_write2_b32 v60, v56, v57 offset0:8 offset1:74
	s_waitcnt vmcnt(8)
	ds_write2_b32 v60, v58, v59 offset0:140 offset1:206
	v_add_u32_e32 v4, 0x840, v4
	v_lshl_add_u64 v[52:53], v[32:33], 0, s[54:55]
	v_lshl_add_u64 v[54:55], v[30:31], 0, s[54:55]
	v_lshl_add_u64 v[56:57], v[28:29], 0, s[54:55]
	v_lshl_add_u64 v[58:59], v[26:27], 0, s[54:55]
	v_lshl_add_u64 v[60:61], v[24:25], 0, s[54:55]
	v_lshl_add_u64 v[62:63], v[22:23], 0, s[54:55]
	v_lshl_add_u64 v[64:65], v[20:21], 0, s[54:55]
	v_lshl_add_u64 v[66:67], v[18:19], 0, s[54:55]
	global_load_dword v52, v[52:53], off nt
	global_load_dword v53, v[54:55], off nt
	global_load_dword v54, v[56:57], off nt
	global_load_dword v55, v[58:59], off nt
	global_load_dword v56, v[60:61], off nt
	global_load_dword v57, v[62:63], off nt
	global_load_dword v58, v[64:65], off nt
	global_load_dword v59, v[66:67], off nt
	s_add_u32 s54, s54, 0x20000
	s_addc_u32 s55, s55, 0
	v_add_u32_e32 v118, 0x400, v4
	s_waitcnt vmcnt(14)
	ds_write2_b32 v4, v110, v111 offset1:66
	s_waitcnt vmcnt(12)
	ds_write2_b32 v4, v112, v113 offset0:132 offset1:198
	s_waitcnt vmcnt(10)
	ds_write2_b32 v118, v114, v115 offset0:8 offset1:74
	s_waitcnt vmcnt(8)
	ds_write2_b32 v118, v116, v117 offset0:140 offset1:206
	v_add_u32_e32 v4, 0x840, v4
	v_lshl_add_u64 v[110:111], v[32:33], 0, s[54:55]
	v_lshl_add_u64 v[112:113], v[30:31], 0, s[54:55]
	v_lshl_add_u64 v[114:115], v[28:29], 0, s[54:55]
	v_lshl_add_u64 v[116:117], v[26:27], 0, s[54:55]
	v_lshl_add_u64 v[118:119], v[24:25], 0, s[54:55]
	v_lshl_add_u64 v[120:121], v[22:23], 0, s[54:55]
	v_lshl_add_u64 v[122:123], v[20:21], 0, s[54:55]
	v_lshl_add_u64 v[124:125], v[18:19], 0, s[54:55]
	global_load_dword v110, v[110:111], off nt
	global_load_dword v111, v[112:113], off nt
	global_load_dword v112, v[114:115], off nt
	global_load_dword v113, v[116:117], off nt
	global_load_dword v114, v[118:119], off nt
	global_load_dword v115, v[120:121], off nt
	global_load_dword v116, v[122:123], off nt
	global_load_dword v117, v[124:125], off nt
	s_add_u32 s54, s54, 0x20000
	s_addc_u32 s55, s55, 0
	v_add_u32_e32 v60, 0x400, v4
	s_waitcnt vmcnt(14)
	ds_write2_b32 v4, v52, v53 offset1:66
	s_waitcnt vmcnt(12)
	ds_write2_b32 v4, v54, v55 offset0:132 offset1:198
	s_waitcnt vmcnt(10)
	ds_write2_b32 v60, v56, v57 offset0:8 offset1:74
	s_waitcnt vmcnt(8)
	ds_write2_b32 v60, v58, v59 offset0:140 offset1:206
	v_add_u32_e32 v4, 0x840, v4
	v_add_u32_e32 v118, 0x400, v4
	s_waitcnt vmcnt(6)
	ds_write2_b32 v4, v110, v111 offset1:66
	s_waitcnt vmcnt(4)
	ds_write2_b32 v4, v112, v113 offset0:132 offset1:198
	s_waitcnt vmcnt(2)
	ds_write2_b32 v118, v114, v115 offset0:8 offset1:74
	s_waitcnt vmcnt(0)
	ds_write2_b32 v118, v116, v117 offset0:140 offset1:206
	v_add_u32_e32 v4, 0x840, v4
	s_lshl_b32 s54, s68, 5
	s_waitcnt lgkmcnt(0)
	s_add_i32 s6, s68, 0xb000
	s_and_b32 s54, s54, 0x7e0
	ds_read2_b32 v[22:23], v37 offset0:33 offset1:41
	ds_read2_b32 v[24:25], v37 offset1:8
	ds_read2_b32 v[26:27], v37 offset0:66 offset1:74
	ds_read2_b32 v[28:29], v37 offset0:99 offset1:107
	ds_read2_b32 v[30:31], v37 offset0:132 offset1:140
	ds_read2_b32 v[32:33], v37 offset0:165 offset1:173
	ds_read2_b32 v[52:53], v37 offset0:198 offset1:206
	ds_read2_b32 v[54:55], v37 offset0:231 offset1:239
	s_and_b32 s6, s6, 0xffc0
	v_or_b32_e32 v4, s54, v36
	s_lshl_b32 s6, s6, 1
	v_mul_u32_u24_e32 v4, 0xa00, v4
	v_lshl_add_u64 v[56:57], v[10:11], 0, s[6:7]
	v_lshlrev_b32_e32 v4, 1, v4
	v_lshl_add_u64 v[58:59], v[56:57], 0, v[4:5]
	v_or_b32_e32 v4, s54, v38
	s_waitcnt lgkmcnt(6)
	v_cvt_pk_bf16_f32 v18, v24, v22
	s_waitcnt lgkmcnt(4)
	v_cvt_pk_bf16_f32 v19, v26, v28
	s_waitcnt lgkmcnt(2)
	v_cvt_pk_bf16_f32 v20, v30, v32
	s_waitcnt lgkmcnt(0)
	v_cvt_pk_bf16_f32 v21, v52, v54
	v_mul_u32_u24_e32 v4, 0xa00, v4
	global_store_dwordx4 v[58:59], v[18:21], off nt
	v_lshlrev_b32_e32 v4, 1, v4
	s_nop 0
	v_cvt_pk_bf16_f32 v18, v25, v23
	v_cvt_pk_bf16_f32 v19, v27, v29
	v_cvt_pk_bf16_f32 v20, v31, v33
	v_cvt_pk_bf16_f32 v21, v53, v55
	v_lshl_add_u64 v[22:23], v[56:57], 0, v[4:5]
	ds_read2_b32 v[24:25], v37 offset0:16 offset1:24
	ds_read2_b32 v[26:27], v37 offset0:49 offset1:57
	ds_read2_b32 v[28:29], v37 offset0:82 offset1:90
	ds_read2_b32 v[30:31], v37 offset0:115 offset1:123
	ds_read2_b32 v[32:33], v37 offset0:148 offset1:156
	ds_read2_b32 v[52:53], v37 offset0:181 offset1:189
	ds_read2_b32 v[54:55], v37 offset0:214 offset1:222
	ds_read2_b32 v[58:59], v37 offset0:247 offset1:255
	v_or_b32_e32 v4, s54, v39
	v_mul_u32_u24_e32 v4, 0xa00, v4
	v_lshlrev_b32_e32 v4, 1, v4
	global_store_dwordx4 v[22:23], v[18:21], off nt
	v_lshl_add_u64 v[22:23], v[56:57], 0, v[4:5]
	v_or_b32_e32 v4, s54, v40
	v_mul_u32_u24_e32 v4, 0xa00, v4
	s_waitcnt lgkmcnt(6)
	v_cvt_pk_bf16_f32 v18, v24, v26
	s_waitcnt lgkmcnt(4)
	v_cvt_pk_bf16_f32 v19, v28, v30
	s_waitcnt lgkmcnt(2)
	v_cvt_pk_bf16_f32 v20, v32, v52
	s_waitcnt lgkmcnt(0)
	v_cvt_pk_bf16_f32 v21, v54, v58
	v_lshlrev_b32_e32 v4, 1, v4
	global_store_dwordx4 v[22:23], v[18:21], off nt
	v_lshl_add_u64 v[22:23], v[56:57], 0, v[4:5]
	s_nop 0
	v_cvt_pk_bf16_f32 v18, v25, v27
	v_cvt_pk_bf16_f32 v19, v29, v31
	v_cvt_pk_bf16_f32 v20, v33, v53
	v_cvt_pk_bf16_f32 v21, v55, v59
	global_store_dwordx4 v[22:23], v[18:21], off nt
	s_waitcnt lgkmcnt(0)

.LBB0_31:
	v_lshl_add_u64 v[52:53], v[32:33], 0, s[54:55]
	v_lshl_add_u64 v[54:55], v[30:31], 0, s[54:55]
	v_lshl_add_u64 v[56:57], v[28:29], 0, s[54:55]
	v_lshl_add_u64 v[58:59], v[26:27], 0, s[54:55]
	v_lshl_add_u64 v[60:61], v[24:25], 0, s[54:55]
	v_lshl_add_u64 v[62:63], v[22:23], 0, s[54:55]
	v_lshl_add_u64 v[64:65], v[20:21], 0, s[54:55]
	v_lshl_add_u64 v[66:67], v[18:19], 0, s[54:55]
	global_load_dword v51, v[52:53], off nt
	global_load_dword v52, v[54:55], off nt
	global_load_dword v53, v[56:57], off nt
	global_load_dword v54, v[58:59], off nt
	global_load_dword v55, v[60:61], off nt
	global_load_dword v56, v[62:63], off nt
	global_load_dword v57, v[64:65], off nt
	global_load_dword v58, v[66:67], off nt
	s_add_u32 s54, s54, 0x20000
	s_addc_u32 s55, s55, 0
	v_lshl_add_u64 v[110:111], v[32:33], 0, s[54:55]
	v_lshl_add_u64 v[112:113], v[30:31], 0, s[54:55]
	v_lshl_add_u64 v[114:115], v[28:29], 0, s[54:55]
	v_lshl_add_u64 v[116:117], v[26:27], 0, s[54:55]
	v_lshl_add_u64 v[118:119], v[24:25], 0, s[54:55]
	v_lshl_add_u64 v[120:121], v[22:23], 0, s[54:55]
	v_lshl_add_u64 v[122:123], v[20:21], 0, s[54:55]
	v_lshl_add_u64 v[124:125], v[18:19], 0, s[54:55]
	global_load_dword v109, v[110:111], off nt
	global_load_dword v110, v[112:113], off nt
	global_load_dword v111, v[114:115], off nt
	global_load_dword v112, v[116:117], off nt
	global_load_dword v113, v[118:119], off nt
	global_load_dword v114, v[120:121], off nt
	global_load_dword v115, v[122:123], off nt
	global_load_dword v116, v[124:125], off nt
	s_add_u32 s54, s54, 0x20000
	s_addc_u32 s55, s55, 0
	v_add_u32_e32 v59, 0x400, v4
	s_waitcnt vmcnt(14)
	ds_write2_b32 v4, v51, v52 offset1:66
	s_waitcnt vmcnt(12)
	ds_write2_b32 v4, v53, v54 offset0:132 offset1:198
	s_waitcnt vmcnt(10)
	ds_write2_b32 v59, v55, v56 offset0:8 offset1:74
	s_waitcnt vmcnt(8)
	ds_write2_b32 v59, v57, v58 offset0:140 offset1:206
	v_add_u32_e32 v4, 0x840, v4
	v_lshl_add_u64 v[52:53], v[32:33], 0, s[54:55]
	v_lshl_add_u64 v[54:55], v[30:31], 0, s[54:55]
	v_lshl_add_u64 v[56:57], v[28:29], 0, s[54:55]
	v_lshl_add_u64 v[58:59], v[26:27], 0, s[54:55]
	v_lshl_add_u64 v[60:61], v[24:25], 0, s[54:55]
	v_lshl_add_u64 v[62:63], v[22:23], 0, s[54:55]
	v_lshl_add_u64 v[64:65], v[20:21], 0, s[54:55]
	v_lshl_add_u64 v[66:67], v[18:19], 0, s[54:55]
	global_load_dword v51, v[52:53], off nt
	global_load_dword v52, v[54:55], off nt
	global_load_dword v53, v[56:57], off nt
	global_load_dword v54, v[58:59], off nt
	global_load_dword v55, v[60:61], off nt
	global_load_dword v56, v[62:63], off nt
	global_load_dword v57, v[64:65], off nt
	global_load_dword v58, v[66:67], off nt
	s_add_u32 s54, s54, 0x20000
	s_addc_u32 s55, s55, 0
	v_add_u32_e32 v117, 0x400, v4
	s_waitcnt vmcnt(14)
	ds_write2_b32 v4, v109, v110 offset1:66
	s_waitcnt vmcnt(12)
	ds_write2_b32 v4, v111, v112 offset0:132 offset1:198
	s_waitcnt vmcnt(10)
	ds_write2_b32 v117, v113, v114 offset0:8 offset1:74
	s_waitcnt vmcnt(8)
	ds_write2_b32 v117, v115, v116 offset0:140 offset1:206
	v_add_u32_e32 v4, 0x840, v4
	v_lshl_add_u64 v[110:111], v[32:33], 0, s[54:55]
	v_lshl_add_u64 v[112:113], v[30:31], 0, s[54:55]
	v_lshl_add_u64 v[114:115], v[28:29], 0, s[54:55]
	v_lshl_add_u64 v[116:117], v[26:27], 0, s[54:55]
	v_lshl_add_u64 v[118:119], v[24:25], 0, s[54:55]
	v_lshl_add_u64 v[120:121], v[22:23], 0, s[54:55]
	v_lshl_add_u64 v[122:123], v[20:21], 0, s[54:55]
	v_lshl_add_u64 v[124:125], v[18:19], 0, s[54:55]
	global_load_dword v109, v[110:111], off nt
	global_load_dword v110, v[112:113], off nt
	global_load_dword v111, v[114:115], off nt
	global_load_dword v112, v[116:117], off nt
	global_load_dword v113, v[118:119], off nt
	global_load_dword v114, v[120:121], off nt
	global_load_dword v115, v[122:123], off nt
	global_load_dword v116, v[124:125], off nt
	s_add_u32 s54, s54, 0x20000
	s_addc_u32 s55, s55, 0
	v_add_u32_e32 v59, 0x400, v4
	s_waitcnt vmcnt(14)
	ds_write2_b32 v4, v51, v52 offset1:66
	s_waitcnt vmcnt(12)
	ds_write2_b32 v4, v53, v54 offset0:132 offset1:198
	s_waitcnt vmcnt(10)
	ds_write2_b32 v59, v55, v56 offset0:8 offset1:74
	s_waitcnt vmcnt(8)
	ds_write2_b32 v59, v57, v58 offset0:140 offset1:206
	v_add_u32_e32 v4, 0x840, v4
	v_add_u32_e32 v117, 0x400, v4
	s_waitcnt vmcnt(6)
	ds_write2_b32 v4, v109, v110 offset1:66
	s_waitcnt vmcnt(4)
	ds_write2_b32 v4, v111, v112 offset0:132 offset1:198
	s_waitcnt vmcnt(2)
	ds_write2_b32 v117, v113, v114 offset0:8 offset1:74
	s_waitcnt vmcnt(0)
	ds_write2_b32 v117, v115, v116 offset0:140 offset1:206
	v_add_u32_e32 v4, 0x840, v4
	s_lshl_b32 s54, s68, 5
	s_waitcnt lgkmcnt(0)
	s_add_i32 s6, s68, 0xb400
	s_and_b32 s54, s54, 0x7e0
	ds_read2_b32 v[22:23], v37 offset0:33 offset1:41
	ds_read2_b32 v[24:25], v37 offset1:8
	ds_read2_b32 v[26:27], v37 offset0:66 offset1:74
	ds_read2_b32 v[28:29], v37 offset0:99 offset1:107
	ds_read2_b32 v[30:31], v37 offset0:132 offset1:140
	ds_read2_b32 v[32:33], v37 offset0:165 offset1:173
	ds_read2_b32 v[52:53], v37 offset0:198 offset1:206
	ds_read2_b32 v[54:55], v37 offset0:231 offset1:239
	s_and_b32 s6, s6, 0xffc0
	v_or_b32_e32 v4, s54, v36
	s_lshl_b32 s6, s6, 1
	v_mul_u32_u24_e32 v4, 0xa00, v4
	v_lshl_add_u64 v[56:57], v[12:13], 0, s[6:7]
	v_lshlrev_b32_e32 v4, 1, v4
	v_lshl_add_u64 v[58:59], v[56:57], 0, v[4:5]
	v_or_b32_e32 v4, s54, v38
	s_waitcnt lgkmcnt(6)
	v_cvt_pk_bf16_f32 v18, v24, v22
	s_waitcnt lgkmcnt(4)
	v_cvt_pk_bf16_f32 v19, v26, v28
	s_waitcnt lgkmcnt(2)
	v_cvt_pk_bf16_f32 v20, v30, v32
	s_waitcnt lgkmcnt(0)
	v_cvt_pk_bf16_f32 v21, v52, v54
	v_mul_u32_u24_e32 v4, 0xa00, v4
	global_store_dwordx4 v[58:59], v[18:21], off nt
	v_lshlrev_b32_e32 v4, 1, v4
	s_nop 0
	v_cvt_pk_bf16_f32 v18, v25, v23
	v_cvt_pk_bf16_f32 v19, v27, v29
	v_cvt_pk_bf16_f32 v20, v31, v33
	v_cvt_pk_bf16_f32 v21, v53, v55
	v_lshl_add_u64 v[22:23], v[56:57], 0, v[4:5]
	ds_read2_b32 v[24:25], v37 offset0:16 offset1:24
	ds_read2_b32 v[26:27], v37 offset0:49 offset1:57
	ds_read2_b32 v[28:29], v37 offset0:82 offset1:90
	ds_read2_b32 v[30:31], v37 offset0:115 offset1:123
	ds_read2_b32 v[32:33], v37 offset0:148 offset1:156
	ds_read2_b32 v[52:53], v37 offset0:181 offset1:189
	ds_read2_b32 v[54:55], v37 offset0:214 offset1:222
	ds_read2_b32 v[58:59], v37 offset0:247 offset1:255
	v_or_b32_e32 v4, s54, v39
	v_mul_u32_u24_e32 v4, 0xa00, v4
	v_lshlrev_b32_e32 v4, 1, v4
	global_store_dwordx4 v[22:23], v[18:21], off nt
	v_lshl_add_u64 v[22:23], v[56:57], 0, v[4:5]
	v_or_b32_e32 v4, s54, v40
	v_mul_u32_u24_e32 v4, 0xa00, v4
	s_waitcnt lgkmcnt(6)
	v_cvt_pk_bf16_f32 v18, v24, v26
	s_waitcnt lgkmcnt(4)
	v_cvt_pk_bf16_f32 v19, v28, v30
	s_waitcnt lgkmcnt(2)
	v_cvt_pk_bf16_f32 v20, v32, v52
	s_waitcnt lgkmcnt(0)
	v_cvt_pk_bf16_f32 v21, v54, v58
	v_lshlrev_b32_e32 v4, 1, v4
	global_store_dwordx4 v[22:23], v[18:21], off nt
	v_lshl_add_u64 v[22:23], v[56:57], 0, v[4:5]
	s_nop 0
	v_cvt_pk_bf16_f32 v18, v25, v27
	v_cvt_pk_bf16_f32 v19, v29, v31
	v_cvt_pk_bf16_f32 v20, v33, v53
	v_cvt_pk_bf16_f32 v21, v55, v59
	global_store_dwordx4 v[22:23], v[18:21], off nt
	s_waitcnt lgkmcnt(0)

.LBB0_36:
	v_lshl_add_u64 v[52:53], v[32:33], 0, s[54:55]
	v_lshl_add_u64 v[54:55], v[30:31], 0, s[54:55]
	v_lshl_add_u64 v[56:57], v[28:29], 0, s[54:55]
	v_lshl_add_u64 v[58:59], v[26:27], 0, s[54:55]
	v_lshl_add_u64 v[60:61], v[24:25], 0, s[54:55]
	v_lshl_add_u64 v[62:63], v[22:23], 0, s[54:55]
	v_lshl_add_u64 v[64:65], v[20:21], 0, s[54:55]
	v_lshl_add_u64 v[66:67], v[18:19], 0, s[54:55]
	global_load_dword v51, v[52:53], off nt
	global_load_dword v52, v[54:55], off nt
	global_load_dword v53, v[56:57], off nt
	global_load_dword v54, v[58:59], off nt
	global_load_dword v55, v[60:61], off nt
	global_load_dword v56, v[62:63], off nt
	global_load_dword v57, v[64:65], off nt
	global_load_dword v58, v[66:67], off nt
	s_add_u32 s54, s54, 0x110000
	s_addc_u32 s55, s55, 0
	v_lshl_add_u64 v[110:111], v[32:33], 0, s[54:55]
	v_lshl_add_u64 v[112:113], v[30:31], 0, s[54:55]
	v_lshl_add_u64 v[114:115], v[28:29], 0, s[54:55]
	v_lshl_add_u64 v[116:117], v[26:27], 0, s[54:55]
	v_lshl_add_u64 v[118:119], v[24:25], 0, s[54:55]
	v_lshl_add_u64 v[120:121], v[22:23], 0, s[54:55]
	v_lshl_add_u64 v[122:123], v[20:21], 0, s[54:55]
	v_lshl_add_u64 v[124:125], v[18:19], 0, s[54:55]
	global_load_dword v109, v[110:111], off nt
	global_load_dword v110, v[112:113], off nt
	global_load_dword v111, v[114:115], off nt
	global_load_dword v112, v[116:117], off nt
	global_load_dword v113, v[118:119], off nt
	global_load_dword v114, v[120:121], off nt
	global_load_dword v115, v[122:123], off nt
	global_load_dword v116, v[124:125], off nt
	s_add_u32 s54, s54, 0x110000
	s_addc_u32 s55, s55, 0
	v_add_u32_e32 v59, 0x400, v4
	s_waitcnt vmcnt(14)
	ds_write2_b32 v4, v51, v52 offset1:66
	s_waitcnt vmcnt(12)
	ds_write2_b32 v4, v53, v54 offset0:132 offset1:198
	s_waitcnt vmcnt(10)
	ds_write2_b32 v59, v55, v56 offset0:8 offset1:74
	s_waitcnt vmcnt(8)
	ds_write2_b32 v59, v57, v58 offset0:140 offset1:206
	v_add_u32_e32 v4, 0x840, v4
	v_lshl_add_u64 v[52:53], v[32:33], 0, s[54:55]
	v_lshl_add_u64 v[54:55], v[30:31], 0, s[54:55]
	v_lshl_add_u64 v[56:57], v[28:29], 0, s[54:55]
	v_lshl_add_u64 v[58:59], v[26:27], 0, s[54:55]
	v_lshl_add_u64 v[60:61], v[24:25], 0, s[54:55]
	v_lshl_add_u64 v[62:63], v[22:23], 0, s[54:55]
	v_lshl_add_u64 v[64:65], v[20:21], 0, s[54:55]
	v_lshl_add_u64 v[66:67], v[18:19], 0, s[54:55]
	global_load_dword v51, v[52:53], off nt
	global_load_dword v52, v[54:55], off nt
	global_load_dword v53, v[56:57], off nt
	global_load_dword v54, v[58:59], off nt
	global_load_dword v55, v[60:61], off nt
	global_load_dword v56, v[62:63], off nt
	global_load_dword v57, v[64:65], off nt
	global_load_dword v58, v[66:67], off nt
	s_add_u32 s54, s54, 0x110000
	s_addc_u32 s55, s55, 0
	v_add_u32_e32 v117, 0x400, v4
	s_waitcnt vmcnt(14)
	ds_write2_b32 v4, v109, v110 offset1:66
	s_waitcnt vmcnt(12)
	ds_write2_b32 v4, v111, v112 offset0:132 offset1:198
	s_waitcnt vmcnt(10)
	ds_write2_b32 v117, v113, v114 offset0:8 offset1:74
	s_waitcnt vmcnt(8)
	ds_write2_b32 v117, v115, v116 offset0:140 offset1:206
	v_add_u32_e32 v4, 0x840, v4
	v_lshl_add_u64 v[110:111], v[32:33], 0, s[54:55]
	v_lshl_add_u64 v[112:113], v[30:31], 0, s[54:55]
	v_lshl_add_u64 v[114:115], v[28:29], 0, s[54:55]
	v_lshl_add_u64 v[116:117], v[26:27], 0, s[54:55]
	v_lshl_add_u64 v[118:119], v[24:25], 0, s[54:55]
	v_lshl_add_u64 v[120:121], v[22:23], 0, s[54:55]
	v_lshl_add_u64 v[122:123], v[20:21], 0, s[54:55]
	v_lshl_add_u64 v[124:125], v[18:19], 0, s[54:55]
	global_load_dword v109, v[110:111], off nt
	global_load_dword v110, v[112:113], off nt
	global_load_dword v111, v[114:115], off nt
	global_load_dword v112, v[116:117], off nt
	global_load_dword v113, v[118:119], off nt
	global_load_dword v114, v[120:121], off nt
	global_load_dword v115, v[122:123], off nt
	global_load_dword v116, v[124:125], off nt
	s_add_u32 s54, s54, 0x110000
	s_addc_u32 s55, s55, 0
	v_add_u32_e32 v59, 0x400, v4
	s_waitcnt vmcnt(14)
	ds_write2_b32 v4, v51, v52 offset1:66
	s_waitcnt vmcnt(12)
	ds_write2_b32 v4, v53, v54 offset0:132 offset1:198
	s_waitcnt vmcnt(10)
	ds_write2_b32 v59, v55, v56 offset0:8 offset1:74
	s_waitcnt vmcnt(8)
	ds_write2_b32 v59, v57, v58 offset0:140 offset1:206
	v_add_u32_e32 v4, 0x840, v4
	v_add_u32_e32 v117, 0x400, v4
	s_waitcnt vmcnt(6)
	ds_write2_b32 v4, v109, v110 offset1:66
	s_waitcnt vmcnt(4)
	ds_write2_b32 v4, v111, v112 offset0:132 offset1:198
	s_waitcnt vmcnt(2)
	ds_write2_b32 v117, v113, v114 offset0:8 offset1:74
	s_waitcnt vmcnt(0)
	ds_write2_b32 v117, v115, v116 offset0:140 offset1:206
	v_add_u32_e32 v4, 0x840, v4
	s_waitcnt lgkmcnt(0)
	s_and_b32 s54, 0xffff, s56
	ds_read2_b32 v[22:23], v37 offset0:33 offset1:41
	ds_read2_b32 v[24:25], v37 offset1:8
	ds_read2_b32 v[26:27], v37 offset0:66 offset1:74
	ds_read2_b32 v[28:29], v37 offset0:99 offset1:107
	ds_read2_b32 v[30:31], v37 offset0:132 offset1:140
	ds_read2_b32 v[32:33], v37 offset0:165 offset1:173
	ds_read2_b32 v[52:53], v37 offset0:198 offset1:206
	ds_read2_b32 v[54:55], v37 offset0:231 offset1:239
	s_and_b32 s6, 0xffff, s6
	v_or_b32_e32 v4, s54, v36
	s_lshl_b32 s6, s6, 1
	v_mul_u32_u24_e32 v4, 0xa00, v4
	v_lshl_add_u64 v[56:57], v[14:15], 0, s[6:7]
	v_lshlrev_b32_e32 v4, 1, v4
	v_lshl_add_u64 v[58:59], v[56:57], 0, v[4:5]
	v_or_b32_e32 v4, s54, v38
	s_waitcnt lgkmcnt(6)
	v_cvt_pk_bf16_f32 v18, v24, v22
	s_waitcnt lgkmcnt(4)
	v_cvt_pk_bf16_f32 v19, v26, v28
	s_waitcnt lgkmcnt(2)
	v_cvt_pk_bf16_f32 v20, v30, v32
	s_waitcnt lgkmcnt(0)
	v_cvt_pk_bf16_f32 v21, v52, v54
	v_mul_u32_u24_e32 v4, 0xa00, v4
	global_store_dwordx4 v[58:59], v[18:21], off nt
	v_lshlrev_b32_e32 v4, 1, v4
	s_nop 0
	v_cvt_pk_bf16_f32 v18, v25, v23
	v_cvt_pk_bf16_f32 v19, v27, v29
	v_cvt_pk_bf16_f32 v20, v31, v33
	v_cvt_pk_bf16_f32 v21, v53, v55
	v_lshl_add_u64 v[22:23], v[56:57], 0, v[4:5]
	ds_read2_b32 v[24:25], v37 offset0:16 offset1:24
	ds_read2_b32 v[26:27], v37 offset0:49 offset1:57
	ds_read2_b32 v[28:29], v37 offset0:82 offset1:90
	ds_read2_b32 v[30:31], v37 offset0:115 offset1:123
	ds_read2_b32 v[32:33], v37 offset0:148 offset1:156
	ds_read2_b32 v[52:53], v37 offset0:181 offset1:189
	ds_read2_b32 v[54:55], v37 offset0:214 offset1:222
	ds_read2_b32 v[58:59], v37 offset0:247 offset1:255
	v_or_b32_e32 v4, s54, v39
	v_mul_u32_u24_e32 v4, 0xa00, v4
	v_lshlrev_b32_e32 v4, 1, v4
	global_store_dwordx4 v[22:23], v[18:21], off nt
	v_lshl_add_u64 v[22:23], v[56:57], 0, v[4:5]
	v_or_b32_e32 v4, s54, v40
	v_mul_u32_u24_e32 v4, 0xa00, v4
	s_waitcnt lgkmcnt(6)
	v_cvt_pk_bf16_f32 v18, v24, v26
	s_waitcnt lgkmcnt(4)
	v_cvt_pk_bf16_f32 v19, v28, v30
	s_waitcnt lgkmcnt(2)
	v_cvt_pk_bf16_f32 v20, v32, v52
	s_waitcnt lgkmcnt(0)
	v_cvt_pk_bf16_f32 v21, v54, v58
	v_lshlrev_b32_e32 v4, 1, v4
	global_store_dwordx4 v[22:23], v[18:21], off nt
	v_lshl_add_u64 v[22:23], v[56:57], 0, v[4:5]
	s_nop 0
	v_cvt_pk_bf16_f32 v18, v25, v27
	v_cvt_pk_bf16_f32 v19, v29, v31
	v_cvt_pk_bf16_f32 v20, v33, v53
	v_cvt_pk_bf16_f32 v21, v55, v59
	global_store_dwordx4 v[22:23], v[18:21], off nt
	s_waitcnt lgkmcnt(0)

.LBB0_41:
	v_lshl_add_u64 v[52:53], v[32:33], 0, s[54:55]
	v_lshl_add_u64 v[54:55], v[30:31], 0, s[54:55]
	v_lshl_add_u64 v[56:57], v[28:29], 0, s[54:55]
	v_lshl_add_u64 v[58:59], v[26:27], 0, s[54:55]
	v_lshl_add_u64 v[60:61], v[24:25], 0, s[54:55]
	v_lshl_add_u64 v[62:63], v[22:23], 0, s[54:55]
	v_lshl_add_u64 v[64:65], v[20:21], 0, s[54:55]
	v_lshl_add_u64 v[66:67], v[18:19], 0, s[54:55]
	global_load_dword v51, v[52:53], off nt
	global_load_dword v52, v[54:55], off nt
	global_load_dword v53, v[56:57], off nt
	global_load_dword v54, v[58:59], off nt
	global_load_dword v55, v[60:61], off nt
	global_load_dword v56, v[62:63], off nt
	global_load_dword v57, v[64:65], off nt
	global_load_dword v58, v[66:67], off nt
	s_add_u32 s54, s54, 0x20000
	s_addc_u32 s55, s55, 0
	v_lshl_add_u64 v[110:111], v[32:33], 0, s[54:55]
	v_lshl_add_u64 v[112:113], v[30:31], 0, s[54:55]
	v_lshl_add_u64 v[114:115], v[28:29], 0, s[54:55]
	v_lshl_add_u64 v[116:117], v[26:27], 0, s[54:55]
	v_lshl_add_u64 v[118:119], v[24:25], 0, s[54:55]
	v_lshl_add_u64 v[120:121], v[22:23], 0, s[54:55]
	v_lshl_add_u64 v[122:123], v[20:21], 0, s[54:55]
	v_lshl_add_u64 v[124:125], v[18:19], 0, s[54:55]
	global_load_dword v109, v[110:111], off nt
	global_load_dword v110, v[112:113], off nt
	global_load_dword v111, v[114:115], off nt
	global_load_dword v112, v[116:117], off nt
	global_load_dword v113, v[118:119], off nt
	global_load_dword v114, v[120:121], off nt
	global_load_dword v115, v[122:123], off nt
	global_load_dword v116, v[124:125], off nt
	s_add_u32 s54, s54, 0x20000
	s_addc_u32 s55, s55, 0
	v_add_u32_e32 v59, 0x400, v4
	s_waitcnt vmcnt(14)
	ds_write2_b32 v4, v51, v52 offset1:66
	s_waitcnt vmcnt(12)
	ds_write2_b32 v4, v53, v54 offset0:132 offset1:198
	s_waitcnt vmcnt(10)
	ds_write2_b32 v59, v55, v56 offset0:8 offset1:74
	s_waitcnt vmcnt(8)
	ds_write2_b32 v59, v57, v58 offset0:140 offset1:206
	v_add_u32_e32 v4, 0x840, v4
	v_lshl_add_u64 v[52:53], v[32:33], 0, s[54:55]
	v_lshl_add_u64 v[54:55], v[30:31], 0, s[54:55]
	v_lshl_add_u64 v[56:57], v[28:29], 0, s[54:55]
	v_lshl_add_u64 v[58:59], v[26:27], 0, s[54:55]
	v_lshl_add_u64 v[60:61], v[24:25], 0, s[54:55]
	v_lshl_add_u64 v[62:63], v[22:23], 0, s[54:55]
	v_lshl_add_u64 v[64:65], v[20:21], 0, s[54:55]
	v_lshl_add_u64 v[66:67], v[18:19], 0, s[54:55]
	global_load_dword v51, v[52:53], off nt
	global_load_dword v52, v[54:55], off nt
	global_load_dword v53, v[56:57], off nt
	global_load_dword v54, v[58:59], off nt
	global_load_dword v55, v[60:61], off nt
	global_load_dword v56, v[62:63], off nt
	global_load_dword v57, v[64:65], off nt
	global_load_dword v58, v[66:67], off nt
	s_add_u32 s54, s54, 0x20000
	s_addc_u32 s55, s55, 0
	v_add_u32_e32 v117, 0x400, v4
	s_waitcnt vmcnt(14)
	ds_write2_b32 v4, v109, v110 offset1:66
	s_waitcnt vmcnt(12)
	ds_write2_b32 v4, v111, v112 offset0:132 offset1:198
	s_waitcnt vmcnt(10)
	ds_write2_b32 v117, v113, v114 offset0:8 offset1:74
	s_waitcnt vmcnt(8)
	ds_write2_b32 v117, v115, v116 offset0:140 offset1:206
	v_add_u32_e32 v4, 0x840, v4
	v_lshl_add_u64 v[110:111], v[32:33], 0, s[54:55]
	v_lshl_add_u64 v[112:113], v[30:31], 0, s[54:55]
	v_lshl_add_u64 v[114:115], v[28:29], 0, s[54:55]
	v_lshl_add_u64 v[116:117], v[26:27], 0, s[54:55]
	v_lshl_add_u64 v[118:119], v[24:25], 0, s[54:55]
	v_lshl_add_u64 v[120:121], v[22:23], 0, s[54:55]
	v_lshl_add_u64 v[122:123], v[20:21], 0, s[54:55]
	v_lshl_add_u64 v[124:125], v[18:19], 0, s[54:55]
	global_load_dword v109, v[110:111], off nt
	global_load_dword v110, v[112:113], off nt
	global_load_dword v111, v[114:115], off nt
	global_load_dword v112, v[116:117], off nt
	global_load_dword v113, v[118:119], off nt
	global_load_dword v114, v[120:121], off nt
	global_load_dword v115, v[122:123], off nt
	global_load_dword v116, v[124:125], off nt
	s_add_u32 s54, s54, 0x20000
	s_addc_u32 s55, s55, 0
	v_add_u32_e32 v59, 0x400, v4
	s_waitcnt vmcnt(14)
	ds_write2_b32 v4, v51, v52 offset1:66
	s_waitcnt vmcnt(12)
	ds_write2_b32 v4, v53, v54 offset0:132 offset1:198
	s_waitcnt vmcnt(10)
	ds_write2_b32 v59, v55, v56 offset0:8 offset1:74
	s_waitcnt vmcnt(8)
	ds_write2_b32 v59, v57, v58 offset0:140 offset1:206
	v_add_u32_e32 v4, 0x840, v4
	v_add_u32_e32 v117, 0x400, v4
	s_waitcnt vmcnt(6)
	ds_write2_b32 v4, v109, v110 offset1:66
	s_waitcnt vmcnt(4)
	ds_write2_b32 v4, v111, v112 offset0:132 offset1:198
	s_waitcnt vmcnt(2)
	ds_write2_b32 v117, v113, v114 offset0:8 offset1:74
	s_waitcnt vmcnt(0)
	ds_write2_b32 v117, v115, v116 offset0:140 offset1:206
	v_add_u32_e32 v4, 0x840, v4
	s_add_i32 s6, s68, 0xffffd400
	s_waitcnt lgkmcnt(0)
	s_and_b32 s54, s6, 0x7c0
	s_lshl_b32 s6, s6, 5
	ds_read2_b32 v[22:23], v37 offset0:33 offset1:41
	ds_read2_b32 v[24:25], v37 offset1:8
	ds_read2_b32 v[26:27], v37 offset0:66 offset1:74
	ds_read2_b32 v[28:29], v37 offset0:99 offset1:107
	ds_read2_b32 v[30:31], v37 offset0:132 offset1:140
	ds_read2_b32 v[32:33], v37 offset0:165 offset1:173
	ds_read2_b32 v[52:53], v37 offset0:198 offset1:206
	ds_read2_b32 v[54:55], v37 offset0:231 offset1:239
	s_and_b32 s6, s6, 0x7e0
	s_add_i32 s55, s6, 0x2c00
	s_lshl_b32 s6, s54, 1
	v_or_b32_e32 v4, s55, v36
	v_lshl_add_u64 v[56:57], v[16:17], 0, s[6:7]
	v_lshlrev_b32_e32 v4, 12, v4
	s_waitcnt lgkmcnt(6)
	v_cvt_pk_bf16_f32 v18, v24, v22
	s_waitcnt lgkmcnt(4)
	v_cvt_pk_bf16_f32 v19, v26, v28
	s_waitcnt lgkmcnt(2)
	v_cvt_pk_bf16_f32 v20, v30, v32
	s_waitcnt lgkmcnt(0)
	v_cvt_pk_bf16_f32 v21, v52, v54
	v_lshl_add_u64 v[58:59], v[56:57], 0, v[4:5]
	global_store_dwordx4 v[58:59], v[18:21], off
	v_or_b32_e32 v4, s55, v38
	v_lshlrev_b32_e32 v4, 12, v4
	v_cvt_pk_bf16_f32 v18, v25, v23
	v_cvt_pk_bf16_f32 v19, v27, v29
	v_cvt_pk_bf16_f32 v20, v31, v33
	v_cvt_pk_bf16_f32 v21, v53, v55
	ds_read2_b32 v[24:25], v37 offset0:49 offset1:57
	ds_read2_b32 v[26:27], v37 offset0:16 offset1:24
	ds_read2_b32 v[28:29], v37 offset0:82 offset1:90
	ds_read2_b32 v[30:31], v37 offset0:115 offset1:123
	ds_read2_b32 v[32:33], v37 offset0:148 offset1:156
	ds_read2_b32 v[52:53], v37 offset0:181 offset1:189
	ds_read2_b32 v[54:55], v37 offset0:214 offset1:222
	ds_read2_b32 v[58:59], v37 offset0:247 offset1:255
	v_lshl_add_u64 v[22:23], v[56:57], 0, v[4:5]
	v_or_b32_e32 v4, s55, v39
	v_lshlrev_b32_e32 v4, 12, v4
	global_store_dwordx4 v[22:23], v[18:21], off
	v_lshl_add_u64 v[22:23], v[56:57], 0, v[4:5]
	v_or_b32_e32 v4, s55, v40
	s_waitcnt lgkmcnt(6)
	v_cvt_pk_bf16_f32 v18, v26, v24
	s_waitcnt lgkmcnt(4)
	v_cvt_pk_bf16_f32 v19, v28, v30
	s_waitcnt lgkmcnt(2)
	v_cvt_pk_bf16_f32 v20, v32, v52
	s_waitcnt lgkmcnt(0)
	v_cvt_pk_bf16_f32 v21, v54, v58
	v_lshlrev_b32_e32 v4, 12, v4
	global_store_dwordx4 v[22:23], v[18:21], off
	v_lshl_add_u64 v[22:23], v[56:57], 0, v[4:5]
	s_nop 0
	v_cvt_pk_bf16_f32 v18, v27, v25
	v_cvt_pk_bf16_f32 v19, v29, v31
	v_cvt_pk_bf16_f32 v20, v33, v53
	v_cvt_pk_bf16_f32 v21, v55, v59
	global_store_dwordx4 v[22:23], v[18:21], off
	s_waitcnt lgkmcnt(0)

.LBB0_46:
	v_lshl_add_u64 v[52:53], v[32:33], 0, s[56:57]
	v_lshl_add_u64 v[54:55], v[30:31], 0, s[56:57]
	v_lshl_add_u64 v[56:57], v[28:29], 0, s[56:57]
	v_lshl_add_u64 v[58:59], v[26:27], 0, s[56:57]
	v_lshl_add_u64 v[60:61], v[24:25], 0, s[56:57]
	v_lshl_add_u64 v[62:63], v[22:23], 0, s[56:57]
	v_lshl_add_u64 v[64:65], v[20:21], 0, s[56:57]
	v_lshl_add_u64 v[66:67], v[18:19], 0, s[56:57]
	global_load_dword v51, v[52:53], off nt
	global_load_dword v52, v[54:55], off nt
	global_load_dword v53, v[56:57], off nt
	global_load_dword v54, v[58:59], off nt
	global_load_dword v55, v[60:61], off nt
	global_load_dword v56, v[62:63], off nt
	global_load_dword v57, v[64:65], off nt
	global_load_dword v58, v[66:67], off nt
	s_add_u32 s56, s56, 0x110000
	s_addc_u32 s57, s57, 0
	v_lshl_add_u64 v[110:111], v[32:33], 0, s[56:57]
	v_lshl_add_u64 v[112:113], v[30:31], 0, s[56:57]
	v_lshl_add_u64 v[114:115], v[28:29], 0, s[56:57]
	v_lshl_add_u64 v[116:117], v[26:27], 0, s[56:57]
	v_lshl_add_u64 v[118:119], v[24:25], 0, s[56:57]
	v_lshl_add_u64 v[120:121], v[22:23], 0, s[56:57]
	v_lshl_add_u64 v[122:123], v[20:21], 0, s[56:57]
	v_lshl_add_u64 v[124:125], v[18:19], 0, s[56:57]
	global_load_dword v109, v[110:111], off nt
	global_load_dword v110, v[112:113], off nt
	global_load_dword v111, v[114:115], off nt
	global_load_dword v112, v[116:117], off nt
	global_load_dword v113, v[118:119], off nt
	global_load_dword v114, v[120:121], off nt
	global_load_dword v115, v[122:123], off nt
	global_load_dword v116, v[124:125], off nt
	s_add_u32 s56, s56, 0x110000
	s_addc_u32 s57, s57, 0
	v_add_u32_e32 v59, 0x400, v4
	s_waitcnt vmcnt(14)
	ds_write2_b32 v4, v51, v52 offset1:66
	s_waitcnt vmcnt(12)
	ds_write2_b32 v4, v53, v54 offset0:132 offset1:198
	s_waitcnt vmcnt(10)
	ds_write2_b32 v59, v55, v56 offset0:8 offset1:74
	s_waitcnt vmcnt(8)
	ds_write2_b32 v59, v57, v58 offset0:140 offset1:206
	v_add_u32_e32 v4, 0x840, v4
	v_lshl_add_u64 v[52:53], v[32:33], 0, s[56:57]
	v_lshl_add_u64 v[54:55], v[30:31], 0, s[56:57]
	v_lshl_add_u64 v[56:57], v[28:29], 0, s[56:57]
	v_lshl_add_u64 v[58:59], v[26:27], 0, s[56:57]
	v_lshl_add_u64 v[60:61], v[24:25], 0, s[56:57]
	v_lshl_add_u64 v[62:63], v[22:23], 0, s[56:57]
	v_lshl_add_u64 v[64:65], v[20:21], 0, s[56:57]
	v_lshl_add_u64 v[66:67], v[18:19], 0, s[56:57]
	global_load_dword v51, v[52:53], off nt
	global_load_dword v52, v[54:55], off nt
	global_load_dword v53, v[56:57], off nt
	global_load_dword v54, v[58:59], off nt
	global_load_dword v55, v[60:61], off nt
	global_load_dword v56, v[62:63], off nt
	global_load_dword v57, v[64:65], off nt
	global_load_dword v58, v[66:67], off nt
	s_add_u32 s56, s56, 0x110000
	s_addc_u32 s57, s57, 0
	v_add_u32_e32 v117, 0x400, v4
	s_waitcnt vmcnt(14)
	ds_write2_b32 v4, v109, v110 offset1:66
	s_waitcnt vmcnt(12)
	ds_write2_b32 v4, v111, v112 offset0:132 offset1:198
	s_waitcnt vmcnt(10)
	ds_write2_b32 v117, v113, v114 offset0:8 offset1:74
	s_waitcnt vmcnt(8)
	ds_write2_b32 v117, v115, v116 offset0:140 offset1:206
	v_add_u32_e32 v4, 0x840, v4
	v_lshl_add_u64 v[110:111], v[32:33], 0, s[56:57]
	v_lshl_add_u64 v[112:113], v[30:31], 0, s[56:57]
	v_lshl_add_u64 v[114:115], v[28:29], 0, s[56:57]
	v_lshl_add_u64 v[116:117], v[26:27], 0, s[56:57]
	v_lshl_add_u64 v[118:119], v[24:25], 0, s[56:57]
	v_lshl_add_u64 v[120:121], v[22:23], 0, s[56:57]
	v_lshl_add_u64 v[122:123], v[20:21], 0, s[56:57]
	v_lshl_add_u64 v[124:125], v[18:19], 0, s[56:57]
	global_load_dword v109, v[110:111], off nt
	global_load_dword v110, v[112:113], off nt
	global_load_dword v111, v[114:115], off nt
	global_load_dword v112, v[116:117], off nt
	global_load_dword v113, v[118:119], off nt
	global_load_dword v114, v[120:121], off nt
	global_load_dword v115, v[122:123], off nt
	global_load_dword v116, v[124:125], off nt
	s_add_u32 s56, s56, 0x110000
	s_addc_u32 s57, s57, 0
	v_add_u32_e32 v59, 0x400, v4
	s_waitcnt vmcnt(14)
	ds_write2_b32 v4, v51, v52 offset1:66
	s_waitcnt vmcnt(12)
	ds_write2_b32 v4, v53, v54 offset0:132 offset1:198
	s_waitcnt vmcnt(10)
	ds_write2_b32 v59, v55, v56 offset0:8 offset1:74
	s_waitcnt vmcnt(8)
	ds_write2_b32 v59, v57, v58 offset0:140 offset1:206
	v_add_u32_e32 v4, 0x840, v4
	v_add_u32_e32 v117, 0x400, v4
	s_waitcnt vmcnt(6)
	ds_write2_b32 v4, v109, v110 offset1:66
	s_waitcnt vmcnt(4)
	ds_write2_b32 v4, v111, v112 offset0:132 offset1:198
	s_waitcnt vmcnt(2)
	ds_write2_b32 v117, v113, v114 offset0:8 offset1:74
	s_waitcnt vmcnt(0)
	ds_write2_b32 v117, v115, v116 offset0:140 offset1:206
	v_add_u32_e32 v4, 0x840, v4
	s_waitcnt lgkmcnt(0)
	ds_read2_b32 v[22:23], v37 offset0:33 offset1:41
	ds_read2_b32 v[24:25], v37 offset1:8
	ds_read2_b32 v[26:27], v37 offset0:66 offset1:74
	ds_read2_b32 v[28:29], v37 offset0:99 offset1:107
	ds_read2_b32 v[30:31], v37 offset0:132 offset1:140
	ds_read2_b32 v[32:33], v37 offset0:165 offset1:173
	ds_read2_b32 v[52:53], v37 offset0:198 offset1:206
	ds_read2_b32 v[54:55], v37 offset0:231 offset1:239
	v_or_b32_e32 v58, s6, v36
	s_ashr_i32 s55, s54, 31
	v_ashrrev_i32_e32 v59, 31, v58
	v_lshl_add_u64 v[56:57], s[54:55], 1, v[16:17]
	v_lshlrev_b64 v[58:59], 12, v[58:59]
	s_waitcnt lgkmcnt(6)
	v_cvt_pk_bf16_f32 v18, v24, v22
	s_waitcnt lgkmcnt(4)
	v_cvt_pk_bf16_f32 v19, v26, v28
	s_waitcnt lgkmcnt(2)
	v_cvt_pk_bf16_f32 v20, v30, v32
	s_waitcnt lgkmcnt(0)
	v_cvt_pk_bf16_f32 v21, v52, v54
	v_lshl_add_u64 v[58:59], v[56:57], 0, v[58:59]
	v_or_b32_e32 v22, s6, v38
	global_store_dwordx4 v[58:59], v[18:21], off
	s_nop 1
	v_cvt_pk_bf16_f32 v18, v25, v23
	v_ashrrev_i32_e32 v23, 31, v22
	v_cvt_pk_bf16_f32 v19, v27, v29
	v_cvt_pk_bf16_f32 v20, v31, v33
	v_cvt_pk_bf16_f32 v21, v53, v55
	v_lshlrev_b64 v[22:23], 12, v[22:23]
	ds_read2_b32 v[24:25], v37 offset0:49 offset1:57
	ds_read2_b32 v[26:27], v37 offset0:16 offset1:24
	ds_read2_b32 v[28:29], v37 offset0:82 offset1:90
	ds_read2_b32 v[30:31], v37 offset0:115 offset1:123
	ds_read2_b32 v[32:33], v37 offset0:148 offset1:156
	ds_read2_b32 v[52:53], v37 offset0:181 offset1:189
	ds_read2_b32 v[54:55], v37 offset0:214 offset1:222
	ds_read2_b32 v[58:59], v37 offset0:247 offset1:255
	v_lshl_add_u64 v[22:23], v[56:57], 0, v[22:23]
	global_store_dwordx4 v[22:23], v[18:21], off
	v_or_b32_e32 v22, s6, v39
	v_ashrrev_i32_e32 v23, 31, v22
	v_lshlrev_b64 v[22:23], 12, v[22:23]
	s_waitcnt lgkmcnt(6)
	v_cvt_pk_bf16_f32 v18, v26, v24
	s_waitcnt lgkmcnt(4)
	v_cvt_pk_bf16_f32 v19, v28, v30
	s_waitcnt lgkmcnt(2)
	v_cvt_pk_bf16_f32 v20, v32, v52
	s_waitcnt lgkmcnt(0)
	v_cvt_pk_bf16_f32 v21, v54, v58
	v_lshl_add_u64 v[22:23], v[56:57], 0, v[22:23]
	global_store_dwordx4 v[22:23], v[18:21], off
	v_or_b32_e32 v22, s6, v40
	v_ashrrev_i32_e32 v23, 31, v22
	v_lshlrev_b64 v[22:23], 12, v[22:23]
	v_cvt_pk_bf16_f32 v18, v27, v25
	v_cvt_pk_bf16_f32 v19, v29, v31
	v_cvt_pk_bf16_f32 v20, v33, v53
	v_cvt_pk_bf16_f32 v21, v55, v59
	v_lshl_add_u64 v[22:23], v[56:57], 0, v[22:23]
	global_store_dwordx4 v[22:23], v[18:21], off
	s_waitcnt lgkmcnt(0)
	s_branch .LBB0_9
